# plus chunk-prep triangular inverse: block levels on f32 MFMA (one wave per 16x16 block, product kept in registers, one barrier per level); diagonal-block substitution with LDS reads issued 14 ahead
# speedup vs baseline: 1.0169x; 1.0118x over previous
; #define LAS __attribute__((address_space(3)))
; __device__ __forceinline__ void gdn_prep_item(LAS unsigned char* lds, int item, int b0, PrepRaw& R, int next_item, const bf16_t* qkv, const float* bg, const float* gconv_w, unsigned char* rec, float* gtarr) {
;     ...
;             *(bf16x8*)(rec + REC_AM + ((rt * 2 + s) * 64 + lane) * 16) = pack8(a0, a1);
;         }
;     }
;     __syncthreads();
;     if (tid < 64) { const int blk = tid >> 4, cidx = tid & 15; float x[16];
; #pragma unroll
;         for (int i = 0; i < 16; ++i) x[i] = (i == cidx) ? 1.f : 0.f;
; #pragma unroll
;         for (int i = 1; i < 16; ++i) { float a = 0.f; const LAS float* row = Lf + (16 * blk + i) * LS + 16 * blk;
; #pragma unroll
;             for (int j4 = 0; j4 < (i + 3) / 4; ++j4) { const f32x4 l4 = *(const LAS f32x4*)(row + 4 * j4);
; #pragma unroll
;                 for (int e = 0; e < 4; ++e) if (4 * j4 + e < i) a += l4[e] * x[4 * j4 + e]; }
;             if (i > cidx) x[i] = -a; }
; #pragma unroll
;         for (int i = 0; i < 16; ++i) Tf[(16 * blk + i) * LS + 16 * blk + cidx] = x[i];
;     }
.LBB0_540:
	s_or_b64 exec, exec, s[0:1]
	s_add_i32 s0, s18, 0xfffff9c8
	s_cmpk_lt_i32 s18, 0x638
	s_cselect_b32 s0, s18, s0
	s_cselect_b32 s1, s19, 0
	v_readlane_b32 s36, v245, 19
	v_readlane_b32 s48, v245, 31
	v_readlane_b32 s49, v245, 32
	s_mul_i32 s1, s1, 0x12000
	s_mul_hi_u32 s6, s0, 0x12000
	s_cselect_b32 s5, s64, s49
	s_cselect_b32 s4, s33, s48
	s_add_i32 s6, s6, s1
	s_mul_i32 s0, s0, 0x12000
	v_cvt_pk_bf16_f32 v58, v50, v46
	v_lshlrev_b32_e32 v50, 4, v118
	s_add_u32 s4, s4, s0
	v_lshl_or_b32 v46, s30, 10, v50
	s_addc_u32 s5, s5, s6
	v_cvt_pk_bf16_f32 v59, v47, v48
	v_ashrrev_i32_e32 v47, 31, v46
	v_lshl_add_u64 v[46:47], s[4:5], 0, v[46:47]
	v_add_co_u32_e32 v46, vcc, 0xc000, v46
	v_cvt_pk_bf16_f32 v56, v56, v55
	s_nop 0
	v_addc_co_u32_e32 v47, vcc, 0, v47, vcc
	s_waitcnt lgkmcnt(0)
	v_cvt_pk_bf16_f32 v57, v51, v52
	v_cmp_gt_i32_e32 vcc, 64, v116
	v_readlane_b32 s37, v245, 20
	v_readlane_b32 s38, v245, 21
	v_readlane_b32 s39, v245, 22
	v_readlane_b32 s40, v245, 23
	v_readlane_b32 s41, v245, 24
	v_readlane_b32 s42, v245, 25
	v_readlane_b32 s43, v245, 26
	v_readlane_b32 s44, v245, 27
	v_readlane_b32 s45, v245, 28
	v_readlane_b32 s46, v245, 29
	v_readlane_b32 s47, v245, 30
	v_readlane_b32 s50, v245, 33
	v_readlane_b32 s51, v245, 34
	global_store_dwordx4 v[46:47], v[56:59], off
	s_barrier
	s_and_saveexec_b64 s[6:7], vcc
	s_cbranch_execz .LBB0_542
	v_and_b32_e32 v61, -16, v116
	v_lshlrev_b32_e32 v96, 8, v61
	v_lshl_add_u32 v96, v61, 4, v96
	v_lshl_add_u32 v96, v61, 2, v96
	v_add_u32_e32 v97, 0x11800, v96
	v_lshl_add_u32 v119, v114, 2, v96
	v_add_u32_e32 v119, 0x15c00, v119
	v_cmp_eq_u32_e32 vcc, 0, v114
	s_nop 1
	v_cndmask_b32_e64 v248, 0, 1.0, vcc
	ds_read_b128 v[136:139], v97 offset:272
	ds_read_b128 v[140:143], v97 offset:544
	ds_read_b128 v[144:147], v97 offset:816
	ds_read_b128 v[148:151], v97 offset:1088
	ds_read_b128 v[152:155], v97 offset:1360
	ds_read_b128 v[156:159], v97 offset:1376
	ds_read_b128 v[160:163], v97 offset:1632
	ds_read_b128 v[164:167], v97 offset:1648
	ds_read_b128 v[168:171], v97 offset:1904
	ds_read_b128 v[172:175], v97 offset:1920
	ds_read_b128 v[176:179], v97 offset:2176
	ds_read_b128 v[180:183], v97 offset:2192
	ds_read_b128 v[184:187], v97 offset:2448
	ds_read_b128 v[188:191], v97 offset:2464
	s_waitcnt lgkmcnt(13)
	v_cmp_eq_u32_e64 s[0:1], 1, v114
	v_cmp_gt_u32_e32 vcc, 1, v114
	v_fma_f32 v132, v248, v136, 0
	s_nop 1
	v_cndmask_b32_e64 v249, 0, 1.0, s[0:1]
	v_cndmask_b32_e64 v249, v249, -v132, vcc
	ds_read_b128 v[192:195], v97 offset:2480
	s_waitcnt lgkmcnt(13)
	v_cmp_eq_u32_e64 s[0:1], 2, v114
	v_cmp_gt_u32_e32 vcc, 2, v114
	v_fma_f32 v133, v248, v140, 0
	v_fmac_f32_e32 v133, v141, v249
	s_nop 1
	v_cndmask_b32_e64 v250, 0, 1.0, s[0:1]
	v_cndmask_b32_e64 v250, v250, -v133, vcc
	ds_read_b128 v[196:199], v97 offset:2720
	s_waitcnt lgkmcnt(13)
	v_cmp_eq_u32_e64 s[0:1], 3, v114
	v_cmp_gt_u32_e32 vcc, 3, v114
	v_fma_f32 v132, v248, v144, 0
	v_fmac_f32_e32 v132, v145, v249
	v_fmac_f32_e32 v132, v146, v250
	v_cndmask_b32_e64 v251, 0, 1.0, s[0:1]
	v_cndmask_b32_e64 v251, v251, -v132, vcc
	ds_read_b128 v[200:203], v97 offset:2736
	s_waitcnt lgkmcnt(13)
	v_cmp_eq_u32_e64 s[0:1], 4, v114
	v_cmp_gt_u32_e32 vcc, 4, v114
	v_fma_f32 v133, v248, v148, 0
	v_fmac_f32_e32 v133, v149, v249
	v_fmac_f32_e32 v133, v150, v250
	v_fmac_f32_e32 v133, v151, v251
	v_cndmask_b32_e64 v252, 0, 1.0, s[0:1]
	v_cndmask_b32_e64 v252, v252, -v133, vcc
	ds_read_b128 v[204:207], v97 offset:2752
	s_waitcnt lgkmcnt(13)
	v_cmp_eq_u32_e64 s[0:1], 5, v114
	v_cmp_gt_u32_e32 vcc, 5, v114
	v_fma_f32 v132, v248, v152, 0
	v_fmac_f32_e32 v132, v153, v249
	v_fmac_f32_e32 v132, v154, v250
	v_fmac_f32_e32 v132, v155, v251
	ds_read_b128 v[208:211], v97 offset:2992
	s_waitcnt lgkmcnt(13)
	v_fmac_f32_e32 v132, v156, v252
	v_cndmask_b32_e64 v253, 0, 1.0, s[0:1]
	v_cndmask_b32_e64 v253, v253, -v132, vcc
	ds_read_b128 v[212:215], v97 offset:3008
	s_waitcnt lgkmcnt(13)
	v_cmp_eq_u32_e64 s[0:1], 6, v114
	v_cmp_gt_u32_e32 vcc, 6, v114
	v_fma_f32 v133, v248, v160, 0
	v_fmac_f32_e32 v133, v161, v249
	v_fmac_f32_e32 v133, v162, v250
	v_fmac_f32_e32 v133, v163, v251
	ds_read_b128 v[216:219], v97 offset:3024
	s_waitcnt lgkmcnt(13)
	v_fmac_f32_e32 v133, v164, v252
	v_fmac_f32_e32 v133, v165, v253
	v_cndmask_b32_e64 v254, 0, 1.0, s[0:1]
	v_cndmask_b32_e64 v254, v254, -v133, vcc
	ds_read_b128 v[64:67], v97 offset:3264
	s_waitcnt lgkmcnt(13)
	v_cmp_eq_u32_e64 s[0:1], 7, v114
	v_cmp_gt_u32_e32 vcc, 7, v114
	v_fma_f32 v132, v248, v168, 0
	v_fmac_f32_e32 v132, v169, v249
	v_fmac_f32_e32 v132, v170, v250
	v_fmac_f32_e32 v132, v171, v251
	ds_read_b128 v[68:71], v97 offset:3280
	s_waitcnt lgkmcnt(13)
	v_fmac_f32_e32 v132, v172, v252
	v_fmac_f32_e32 v132, v173, v253
	v_fmac_f32_e32 v132, v174, v254
	v_cndmask_b32_e64 v255, 0, 1.0, s[0:1]
	v_cndmask_b32_e64 v255, v255, -v132, vcc
	ds_read_b128 v[72:75], v97 offset:3296
	s_waitcnt lgkmcnt(13)
	v_cmp_eq_u32_e64 s[0:1], 8, v114
	v_cmp_gt_u32_e32 vcc, 8, v114
	v_fma_f32 v133, v248, v176, 0
	v_fmac_f32_e32 v133, v177, v249
	v_fmac_f32_e32 v133, v178, v250
	v_fmac_f32_e32 v133, v179, v251
	ds_read_b128 v[76:79], v97 offset:3536
	s_waitcnt lgkmcnt(13)
	v_fmac_f32_e32 v133, v180, v252
	v_fmac_f32_e32 v133, v181, v253
	v_fmac_f32_e32 v133, v182, v254
	v_fmac_f32_e32 v133, v183, v255
	v_cndmask_b32_e64 v240, 0, 1.0, s[0:1]
	v_cndmask_b32_e64 v240, v240, -v133, vcc
	ds_read_b128 v[80:83], v97 offset:3552
	s_waitcnt lgkmcnt(13)
	v_cmp_eq_u32_e64 s[0:1], 9, v114
	v_cmp_gt_u32_e32 vcc, 9, v114
	v_fma_f32 v132, v248, v184, 0
	v_fmac_f32_e32 v132, v185, v249
	v_fmac_f32_e32 v132, v186, v250
	v_fmac_f32_e32 v132, v187, v251
	ds_read_b128 v[84:87], v97 offset:3568
	s_waitcnt lgkmcnt(13)
; #define LAS __attribute__((address_space(3)))
; __device__ __forceinline__ void gdn_prep_item(LAS unsigned char* lds, int item, int b0, PrepRaw& R, int next_item, const bf16_t* qkv, const float* bg, const float* gconv_w, unsigned char* rec, float* gtarr) {
;     ...
;     if (tid < 64) { const int blk = tid >> 4, cidx = tid & 15; float x[16];
; #pragma unroll
;         for (int i = 0; i < 16; ++i) x[i] = (i == cidx) ? 1.f : 0.f;
; #pragma unroll
;         for (int i = 1; i < 16; ++i) { float a = 0.f; const LAS float* row = Lf + (16 * blk + i) * LS + 16 * blk;
; #pragma unroll
;             for (int j4 = 0; j4 < (i + 3) / 4; ++j4) { const f32x4 l4 = *(const LAS f32x4*)(row + 4 * j4);
; #pragma unroll
;                 for (int e = 0; e < 4; ++e) if (4 * j4 + e < i) a += l4[e] * x[4 * j4 + e]; }
;             if (i > cidx) x[i] = -a; }
; #pragma unroll
;         for (int i = 0; i < 16; ++i) Tf[(16 * blk + i) * LS + 16 * blk + cidx] = x[i];
;     }
	v_fmac_f32_e32 v132, v188, v252
	v_fmac_f32_e32 v132, v189, v253
	v_fmac_f32_e32 v132, v190, v254
	v_fmac_f32_e32 v132, v191, v255
	ds_read_b128 v[88:91], v97 offset:3584
	s_waitcnt lgkmcnt(13)
	v_fmac_f32_e32 v132, v192, v240
	v_cndmask_b32_e64 v241, 0, 1.0, s[0:1]
	v_cndmask_b32_e64 v241, v241, -v132, vcc
	ds_read_b128 v[92:95], v97 offset:3808
	s_waitcnt lgkmcnt(13)
	v_cmp_eq_u32_e64 s[0:1], 10, v114
	v_cmp_gt_u32_e32 vcc, 10, v114
	v_fma_f32 v133, v248, v196, 0
	v_fmac_f32_e32 v133, v197, v249
	v_fmac_f32_e32 v133, v198, v250
	v_fmac_f32_e32 v133, v199, v251
	ds_read_b128 v[120:123], v97 offset:3824
	s_waitcnt lgkmcnt(13)
	v_fmac_f32_e32 v133, v200, v252
	v_fmac_f32_e32 v133, v201, v253
	v_fmac_f32_e32 v133, v202, v254
	v_fmac_f32_e32 v133, v203, v255
	ds_read_b128 v[124:127], v97 offset:3840
	s_waitcnt lgkmcnt(13)
	v_fmac_f32_e32 v133, v204, v240
	v_fmac_f32_e32 v133, v205, v241
	v_cndmask_b32_e64 v242, 0, 1.0, s[0:1]
	v_cndmask_b32_e64 v242, v242, -v133, vcc
	ds_read_b128 v[128:131], v97 offset:3856
	s_waitcnt lgkmcnt(13)
	v_cmp_eq_u32_e64 s[0:1], 11, v114
	v_cmp_gt_u32_e32 vcc, 11, v114
	v_fma_f32 v132, v248, v208, 0
	v_fmac_f32_e32 v132, v209, v249
	v_fmac_f32_e32 v132, v210, v250
	v_fmac_f32_e32 v132, v211, v251
	ds_read_b128 v[222:225], v97 offset:4080
	s_waitcnt lgkmcnt(13)
	v_fmac_f32_e32 v132, v212, v252
	v_fmac_f32_e32 v132, v213, v253
	v_fmac_f32_e32 v132, v214, v254
	v_fmac_f32_e32 v132, v215, v255
	ds_read_b128 v[226:229], v97 offset:4096
	s_waitcnt lgkmcnt(13)
	v_fmac_f32_e32 v132, v216, v240
	v_fmac_f32_e32 v132, v217, v241
	v_fmac_f32_e32 v132, v218, v242
	v_cndmask_b32_e64 v243, 0, 1.0, s[0:1]
	v_cndmask_b32_e64 v243, v243, -v132, vcc
	ds_read_b128 v[230:233], v97 offset:4112
	s_waitcnt lgkmcnt(13)
	v_cmp_eq_u32_e64 s[0:1], 12, v114
	v_cmp_gt_u32_e32 vcc, 12, v114
	v_fma_f32 v133, v248, v64, 0
	v_fmac_f32_e32 v133, v65, v249
	v_fmac_f32_e32 v133, v66, v250
	v_fmac_f32_e32 v133, v67, v251
	ds_read_b128 v[234:237], v97 offset:4128
	s_waitcnt lgkmcnt(13)
	v_fmac_f32_e32 v133, v68, v252
	v_fmac_f32_e32 v133, v69, v253
	v_fmac_f32_e32 v133, v70, v254
	v_fmac_f32_e32 v133, v71, v255
	s_waitcnt lgkmcnt(12)
	v_fmac_f32_e32 v133, v72, v240
	v_fmac_f32_e32 v133, v73, v241
	v_fmac_f32_e32 v133, v74, v242
	v_fmac_f32_e32 v133, v75, v243
	v_cndmask_b32_e64 v102, 0, 1.0, s[0:1]
	v_cndmask_b32_e64 v102, v102, -v133, vcc
	s_waitcnt lgkmcnt(11)
	v_cmp_eq_u32_e64 s[0:1], 13, v114
	v_cmp_gt_u32_e32 vcc, 13, v114
	v_fma_f32 v132, v248, v76, 0
	v_fmac_f32_e32 v132, v77, v249
	v_fmac_f32_e32 v132, v78, v250
	v_fmac_f32_e32 v132, v79, v251
	s_waitcnt lgkmcnt(10)
	v_fmac_f32_e32 v132, v80, v252
	v_fmac_f32_e32 v132, v81, v253
	v_fmac_f32_e32 v132, v82, v254
	v_fmac_f32_e32 v132, v83, v255
	s_waitcnt lgkmcnt(9)
	v_fmac_f32_e32 v132, v84, v240
	v_fmac_f32_e32 v132, v85, v241
	v_fmac_f32_e32 v132, v86, v242
	v_fmac_f32_e32 v132, v87, v243
	s_waitcnt lgkmcnt(8)
	v_fmac_f32_e32 v132, v88, v102
	v_cndmask_b32_e64 v103, 0, 1.0, s[0:1]
	v_cndmask_b32_e64 v103, v103, -v132, vcc
	s_waitcnt lgkmcnt(7)
	v_cmp_eq_u32_e64 s[0:1], 14, v114
	v_cmp_gt_u32_e32 vcc, 14, v114
	v_fma_f32 v133, v248, v92, 0
	v_fmac_f32_e32 v133, v93, v249
	v_fmac_f32_e32 v133, v94, v250
	v_fmac_f32_e32 v133, v95, v251
	s_waitcnt lgkmcnt(6)
	v_fmac_f32_e32 v133, v120, v252
	v_fmac_f32_e32 v133, v121, v253
	v_fmac_f32_e32 v133, v122, v254
	v_fmac_f32_e32 v133, v123, v255
	s_waitcnt lgkmcnt(5)
	v_fmac_f32_e32 v133, v124, v240
	v_fmac_f32_e32 v133, v125, v241
	v_fmac_f32_e32 v133, v126, v242
	v_fmac_f32_e32 v133, v127, v243
	s_waitcnt lgkmcnt(4)
	v_fmac_f32_e32 v133, v128, v102
	v_fmac_f32_e32 v133, v129, v103
	v_cndmask_b32_e64 v104, 0, 1.0, s[0:1]
	v_cndmask_b32_e64 v104, v104, -v133, vcc
	s_waitcnt lgkmcnt(3)
	v_cmp_eq_u32_e64 s[0:1], 15, v114
	v_cmp_gt_u32_e32 vcc, 15, v114
	v_fma_f32 v132, v248, v222, 0
	v_fmac_f32_e32 v132, v223, v249
	v_fmac_f32_e32 v132, v224, v250
	v_fmac_f32_e32 v132, v225, v251
	s_waitcnt lgkmcnt(2)
	v_fmac_f32_e32 v132, v226, v252
	v_fmac_f32_e32 v132, v227, v253
	v_fmac_f32_e32 v132, v228, v254
	v_fmac_f32_e32 v132, v229, v255
	s_waitcnt lgkmcnt(1)
	v_fmac_f32_e32 v132, v230, v240
	v_fmac_f32_e32 v132, v231, v241
	v_fmac_f32_e32 v132, v232, v242
	v_fmac_f32_e32 v132, v233, v243
	s_waitcnt lgkmcnt(0)
	v_fmac_f32_e32 v132, v234, v102
	v_fmac_f32_e32 v132, v235, v103
	v_fmac_f32_e32 v132, v236, v104
	v_cndmask_b32_e64 v105, 0, 1.0, s[0:1]
	v_cndmask_b32_e64 v105, v105, -v132, vcc
	ds_write_b32 v119, v248
	ds_write_b32 v119, v249 offset:272
	ds_write_b32 v119, v250 offset:544
	ds_write_b32 v119, v251 offset:816
	ds_write_b32 v119, v252 offset:1088
	ds_write_b32 v119, v253 offset:1360
	ds_write_b32 v119, v254 offset:1632
	ds_write_b32 v119, v255 offset:1904
	ds_write_b32 v119, v240 offset:2176
	ds_write_b32 v119, v241 offset:2448
	ds_write_b32 v119, v242 offset:2720
	ds_write_b32 v119, v243 offset:2992
	ds_write_b32 v119, v102 offset:3264
	ds_write_b32 v119, v103 offset:3536
	ds_write_b32 v119, v104 offset:3808
	ds_write_b32 v119, v105 offset:4080
; #define LAS __attribute__((address_space(3)))
; __device__ __forceinline__ void gdn_prep_item(LAS unsigned char* lds, int item, int b0, PrepRaw& R, int next_item, const bf16_t* qkv, const float* bg, const float* gconv_w, unsigned char* rec, float* gtarr) {
;     ...
;     __syncthreads();
; #pragma unroll 1
;     for (int k = 1; k < 4; ++k) {
;         const int ntask = (4 - k) * 64;
;         if (tid < ntask) { const int bi = tid >> 6, r = (tid >> 2) & 15, cq = tid & 3, a = bi + k; f32x4 X = (f32x4){0.f, 0.f, 0.f, 0.f};
;             for (int m = bi; m < a; ++m)
; #pragma unroll
;                 for (int j4 = 0; j4 < 4; ++j4) { const f32x4 l4 = *(const LAS f32x4*)(Lf + (16 * a + r) * LS + 16 * m + 4 * j4);
; #pragma unroll
;                     for (int e = 0; e < 4; ++e) X += l4[e] * *(const LAS f32x4*)(Tf + (16 * m + 4 * j4 + e) * LS + 16 * bi + 4 * cq); }
;             *(LAS f32x4*)(Xs + bi * 256 + r * 16 + 4 * cq) = X; }
;         __syncthreads();
;         if (tid < ntask) { const int bi = tid >> 6, r = (tid >> 2) & 15, cq = tid & 3, a = bi + k; f32x4 v = (f32x4){0.f, 0.f, 0.f, 0.f};
; #pragma unroll
;             for (int j4 = 0; j4 < 4; ++j4) { const f32x4 t4 = *(const LAS f32x4*)(Tf + (16 * a + r) * LS + 16 * a + 4 * j4);
; #pragma unroll
;                 for (int e = 0; e < 4; ++e) v += t4[e] * *(const LAS f32x4*)(Xs + bi * 256 + (4 * j4 + e) * 16 + 4 * cq); }
;             *(LAS f32x4*)(Tf + (16 * a + r) * LS + 16 * bi + 4 * cq) = -v; }
;         __syncthreads();
;     }
.LBB0_542:
	s_or_b64 exec, exec, s[6:7]
	s_movk_i32 s0, 0x1140
	v_bfe_u32 v52, v116, 2, 4
	v_and_b32_e32 v46, 0xffffffc0, v116
	v_and_b32_e32 v53, 48, v54
	v_lshl_add_u32 v56, v117, 10, s27
	v_mul_lo_u32 v47, v117, s0
	v_add3_u32 v55, s22, v46, v53
	v_lshl_add_u32 v48, v52, 6, v56
	v_mad_u32_u24 v57, v52, s26, v47
	v_mad_u64_u32 v[46:47], s[0:1], v117, s17, v[46:47]
	v_lshrrev_b32_e32 v51, 2, v116
	v_or_b32_e32 v58, v46, v53
	s_mov_b32 s18, 1
	v_add_u32_e32 v59, v48, v53
	v_readfirstlane_b32 s98, v117
	v_and_b32_e32 v139, 15, v116
	v_bfe_u32 v137, v116, 4, 2
	v_lshlrev_b32_e32 v136, 8, v139
	v_lshl_add_u32 v136, v139, 4, v136
	v_lshl_add_u32 v136, v137, 4, v136
	v_lshlrev_b32_e32 v138, 10, v137
	v_lshl_add_u32 v138, v137, 6, v138
	v_lshl_add_u32 v137, v139, 2, v138
	s_mulk_i32 s98, 0x1140
	v_add_u32_e32 v138, 0x15c00, v136
	v_add_u32_e32 v136, 0x11800, v136
	v_add_u32_e32 v137, 0x15c00, v137
	v_add_u32_e32 v136, s98, v136
	v_add_u32_e32 v137, s98, v137
	v_add_u32_e32 v138, s98, v138
	s_waitcnt lgkmcnt(0)
	s_barrier
	s_cmpk_gt_u32 s98, 0x2280
	s_cbranch_scc1 .Llvm_1
	ds_read_b128 v[140:143], v136 offset:4352
	ds_read_b32 v152, v137
	ds_read_b32 v153, v137 offset:272
	ds_read_b32 v154, v137 offset:544
	ds_read_b32 v155, v137 offset:816
	ds_read_b128 v[164:167], v138 offset:4416
	s_waitcnt lgkmcnt(4)
	v_mfma_f32_16x16x4_f32 v[168:171], v140, v152, 0
	s_waitcnt lgkmcnt(3)
	v_mfma_f32_16x16x4_f32 v[168:171], v141, v153, v[168:171]
	s_waitcnt lgkmcnt(2)
	v_mfma_f32_16x16x4_f32 v[168:171], v142, v154, v[168:171]
	s_waitcnt lgkmcnt(1)
	v_mfma_f32_16x16x4_f32 v[168:171], v143, v155, v[168:171]
	s_waitcnt lgkmcnt(0)
	v_xor_b32_e32 v164, 0x80000000, v164
	v_xor_b32_e32 v165, 0x80000000, v165
	v_xor_b32_e32 v166, 0x80000000, v166
	v_xor_b32_e32 v167, 0x80000000, v167
	s_nop 5
	v_mfma_f32_16x16x4_f32 v[172:175], v164, v168, 0
	v_mfma_f32_16x16x4_f32 v[172:175], v165, v169, v[172:175]
	v_mfma_f32_16x16x4_f32 v[172:175], v166, v170, v[172:175]
	v_mfma_f32_16x16x4_f32 v[172:175], v167, v171, v[172:175]
	s_nop 7
	s_nop 1
	ds_write_b32 v137, v172 offset:4352
	ds_write_b32 v137, v173 offset:4624
	ds_write_b32 v137, v174 offset:4896
	ds_write_b32 v137, v175 offset:5168
.Llvm_1:
	s_waitcnt lgkmcnt(0)
	s_barrier
	s_cmpk_gt_u32 s98, 0x1140
	s_cbranch_scc1 .Llvm_2
	ds_read_b128 v[140:143], v136 offset:8704
	ds_read_b32 v152, v137
	ds_read_b32 v153, v137 offset:272
	ds_read_b32 v154, v137 offset:544
	ds_read_b32 v155, v137 offset:816
	ds_read_b128 v[144:147], v136 offset:8768
	ds_read_b32 v156, v137 offset:4352
	ds_read_b32 v157, v137 offset:4624
	ds_read_b32 v158, v137 offset:4896
	ds_read_b32 v159, v137 offset:5168
	ds_read_b128 v[164:167], v138 offset:8832
	s_waitcnt lgkmcnt(9)
	v_mfma_f32_16x16x4_f32 v[168:171], v140, v152, 0
	s_waitcnt lgkmcnt(8)
	v_mfma_f32_16x16x4_f32 v[168:171], v141, v153, v[168:171]
	s_waitcnt lgkmcnt(7)
	v_mfma_f32_16x16x4_f32 v[168:171], v142, v154, v[168:171]
	s_waitcnt lgkmcnt(6)
	v_mfma_f32_16x16x4_f32 v[168:171], v143, v155, v[168:171]
	s_waitcnt lgkmcnt(4)
	v_mfma_f32_16x16x4_f32 v[168:171], v144, v156, v[168:171]
	s_waitcnt lgkmcnt(3)
	v_mfma_f32_16x16x4_f32 v[168:171], v145, v157, v[168:171]
	s_waitcnt lgkmcnt(2)
	v_mfma_f32_16x16x4_f32 v[168:171], v146, v158, v[168:171]
	s_waitcnt lgkmcnt(1)
	v_mfma_f32_16x16x4_f32 v[168:171], v147, v159, v[168:171]
	s_waitcnt lgkmcnt(0)
	v_xor_b32_e32 v164, 0x80000000, v164
	v_xor_b32_e32 v165, 0x80000000, v165
	v_xor_b32_e32 v166, 0x80000000, v166
	v_xor_b32_e32 v167, 0x80000000, v167
	s_nop 5
	v_mfma_f32_16x16x4_f32 v[172:175], v164, v168, 0
	v_mfma_f32_16x16x4_f32 v[172:175], v165, v169, v[172:175]
	v_mfma_f32_16x16x4_f32 v[172:175], v166, v170, v[172:175]
	v_mfma_f32_16x16x4_f32 v[172:175], v167, v171, v[172:175]
	s_nop 7
	s_nop 1
	ds_write_b32 v137, v172 offset:8704
	ds_write_b32 v137, v173 offset:8976
	ds_write_b32 v137, v174 offset:9248
	ds_write_b32 v137, v175 offset:9520
.Llvm_2:
	s_waitcnt lgkmcnt(0)
	s_barrier
	s_cmpk_gt_u32 s98, 0x0
	s_cbranch_scc1 .Llvm_3
	ds_read_b128 v[140:143], v136 offset:13056
	ds_read_b32 v152, v137
	ds_read_b32 v153, v137 offset:272
	ds_read_b32 v154, v137 offset:544
	ds_read_b32 v155, v137 offset:816
	ds_read_b128 v[144:147], v136 offset:13120
	ds_read_b32 v156, v137 offset:4352
	ds_read_b32 v157, v137 offset:4624
	ds_read_b32 v158, v137 offset:4896
	ds_read_b32 v159, v137 offset:5168
	ds_read_b128 v[148:151], v136 offset:13184
	ds_read_b32 v160, v137 offset:8704
	ds_read_b32 v161, v137 offset:8976
	ds_read_b32 v162, v137 offset:9248
	ds_read_b32 v163, v137 offset:9520
	ds_read_b128 v[164:167], v138 offset:13248
	s_waitcnt lgkmcnt(14)
	v_mfma_f32_16x16x4_f32 v[168:171], v140, v152, 0
	s_waitcnt lgkmcnt(13)
	v_mfma_f32_16x16x4_f32 v[168:171], v141, v153, v[168:171]
	s_waitcnt lgkmcnt(12)
	v_mfma_f32_16x16x4_f32 v[168:171], v142, v154, v[168:171]
	s_waitcnt lgkmcnt(11)
	v_mfma_f32_16x16x4_f32 v[168:171], v143, v155, v[168:171]
	s_waitcnt lgkmcnt(9)
	v_mfma_f32_16x16x4_f32 v[168:171], v144, v156, v[168:171]
	s_waitcnt lgkmcnt(8)
	v_mfma_f32_16x16x4_f32 v[168:171], v145, v157, v[168:171]
	s_waitcnt lgkmcnt(7)
	v_mfma_f32_16x16x4_f32 v[168:171], v146, v158, v[168:171]
	s_waitcnt lgkmcnt(6)
	v_mfma_f32_16x16x4_f32 v[168:171], v147, v159, v[168:171]
	s_waitcnt lgkmcnt(4)
	v_mfma_f32_16x16x4_f32 v[168:171], v148, v160, v[168:171]
	s_waitcnt lgkmcnt(3)
	v_mfma_f32_16x16x4_f32 v[168:171], v149, v161, v[168:171]
	s_waitcnt lgkmcnt(2)
	v_mfma_f32_16x16x4_f32 v[168:171], v150, v162, v[168:171]
	s_waitcnt lgkmcnt(1)
	v_mfma_f32_16x16x4_f32 v[168:171], v151, v163, v[168:171]
	s_waitcnt lgkmcnt(0)
	v_xor_b32_e32 v164, 0x80000000, v164
	v_xor_b32_e32 v165, 0x80000000, v165
	v_xor_b32_e32 v166, 0x80000000, v166
	v_xor_b32_e32 v167, 0x80000000, v167
	s_nop 5
	v_mfma_f32_16x16x4_f32 v[172:175], v164, v168, 0
	v_mfma_f32_16x16x4_f32 v[172:175], v165, v169, v[172:175]
	v_mfma_f32_16x16x4_f32 v[172:175], v166, v170, v[172:175]
	v_mfma_f32_16x16x4_f32 v[172:175], v167, v171, v[172:175]
	s_nop 7
	s_nop 1
	ds_write_b32 v137, v172 offset:13056
	ds_write_b32 v137, v173 offset:13328
	ds_write_b32 v137, v174 offset:13600
	ds_write_b32 v137, v175 offset:13872
.Llvm_3:
	s_waitcnt lgkmcnt(0)
	s_barrier

; #define LAS __attribute__((address_space(3)))
; __device__ __forceinline__ void gdn_prep_item(LAS unsigned char* lds, int item, int b0, PrepRaw& R, int next_item, const bf16_t* qkv, const float* bg, const float* gconv_w, unsigned char* rec, float* gtarr) {
;     ...
;             *(bf16x8*)(rec + REC_AM + ((rt * 2 + s) * 64 + lane) * 16) = pack8(a0, a1);
;         }
;     }
;     __syncthreads();
;     if (tid < 64) { const int blk = tid >> 4, cidx = tid & 15; float x[16];
; #pragma unroll
;         for (int i = 0; i < 16; ++i) x[i] = (i == cidx) ? 1.f : 0.f;
; #pragma unroll
;         for (int i = 1; i < 16; ++i) { float a = 0.f; const LAS float* row = Lf + (16 * blk + i) * LS + 16 * blk;
; #pragma unroll
;             for (int j4 = 0; j4 < (i + 3) / 4; ++j4) { const f32x4 l4 = *(const LAS f32x4*)(row + 4 * j4);
; #pragma unroll
;                 for (int e = 0; e < 4; ++e) if (4 * j4 + e < i) a += l4[e] * x[4 * j4 + e]; }
;             if (i > cidx) x[i] = -a; }
; #pragma unroll
;         for (int i = 0; i < 16; ++i) Tf[(16 * blk + i) * LS + 16 * blk + cidx] = x[i];
;     }
.LBB0_687:
	s_or_b64 exec, exec, s[0:1]
	s_add_i32 s0, s18, 0xfffff9c8
	s_cmpk_lt_i32 s18, 0x638
	s_cselect_b32 s0, s18, s0
	s_cselect_b32 s1, s19, 0
	v_readlane_b32 s36, v245, 19
	v_readlane_b32 s48, v245, 31
	v_readlane_b32 s49, v245, 32
	s_mul_i32 s1, s1, 0x12000
	s_mul_hi_u32 s6, s0, 0x12000
	s_cselect_b32 s5, s64, s49
	s_cselect_b32 s4, s33, s48
	s_add_i32 s6, s6, s1
	s_mul_i32 s0, s0, 0x12000
	v_cvt_pk_bf16_f32 v12, v13, v12
	v_cvt_pk_bf16_f32 v13, v7, v8
	v_lshlrev_b32_e32 v7, 4, v101
	s_add_u32 s4, s4, s0
	s_waitcnt lgkmcnt(0)
	v_cvt_pk_bf16_f32 v14, v6, v2
	v_lshl_or_b32 v2, s20, 10, v7
	s_addc_u32 s5, s5, s6
	v_cvt_pk_bf16_f32 v15, v3, v4
	v_ashrrev_i32_e32 v3, 31, v2
	v_lshl_add_u64 v[2:3], s[4:5], 0, v[2:3]
	v_add_co_u32_e32 v2, vcc, 0xc000, v2
	v_readlane_b32 s37, v245, 20
	s_nop 0
	v_addc_co_u32_e32 v3, vcc, 0, v3, vcc
	v_cmp_gt_i32_e32 vcc, 64, v99
	v_readlane_b32 s38, v245, 21
	v_readlane_b32 s39, v245, 22
	v_readlane_b32 s40, v245, 23
	v_readlane_b32 s41, v245, 24
	v_readlane_b32 s42, v245, 25
	v_readlane_b32 s43, v245, 26
	v_readlane_b32 s44, v245, 27
	v_readlane_b32 s45, v245, 28
	v_readlane_b32 s46, v245, 29
	v_readlane_b32 s47, v245, 30
	v_readlane_b32 s50, v245, 33
	v_readlane_b32 s51, v245, 34
	global_store_dwordx4 v[2:3], v[12:15], off sc0 sc1
	s_barrier
	s_and_saveexec_b64 s[6:7], vcc
	s_cbranch_execz .LBB0_689
	v_and_b32_e32 v61, -16, v99
	v_lshlrev_b32_e32 v96, 8, v61
	v_lshl_add_u32 v96, v61, 4, v96
	v_lshl_add_u32 v96, v61, 2, v96
	v_add_u32_e32 v97, 0x11800, v96
	v_lshl_add_u32 v119, v1, 2, v96
	v_add_u32_e32 v119, 0x15c00, v119
	v_cmp_eq_u32_e32 vcc, 0, v1
	s_nop 1
	v_cndmask_b32_e64 v248, 0, 1.0, vcc
	ds_read_b128 v[136:139], v97 offset:272
	ds_read_b128 v[140:143], v97 offset:544
	ds_read_b128 v[144:147], v97 offset:816
	ds_read_b128 v[148:151], v97 offset:1088
	ds_read_b128 v[152:155], v97 offset:1360
	ds_read_b128 v[156:159], v97 offset:1376
	ds_read_b128 v[160:163], v97 offset:1632
	ds_read_b128 v[164:167], v97 offset:1648
	ds_read_b128 v[168:171], v97 offset:1904
	ds_read_b128 v[172:175], v97 offset:1920
	ds_read_b128 v[176:179], v97 offset:2176
	ds_read_b128 v[180:183], v97 offset:2192
	ds_read_b128 v[184:187], v97 offset:2448
	ds_read_b128 v[188:191], v97 offset:2464
	s_waitcnt lgkmcnt(13)
	v_cmp_eq_u32_e64 s[0:1], 1, v1
	v_cmp_gt_u32_e32 vcc, 1, v1
	v_fma_f32 v132, v248, v136, 0
	s_nop 1
	v_cndmask_b32_e64 v249, 0, 1.0, s[0:1]
	v_cndmask_b32_e64 v249, v249, -v132, vcc
	ds_read_b128 v[192:195], v97 offset:2480
	s_waitcnt lgkmcnt(13)
	v_cmp_eq_u32_e64 s[0:1], 2, v1
	v_cmp_gt_u32_e32 vcc, 2, v1
	v_fma_f32 v133, v248, v140, 0
	v_fmac_f32_e32 v133, v141, v249
	s_nop 1
	v_cndmask_b32_e64 v250, 0, 1.0, s[0:1]
	v_cndmask_b32_e64 v250, v250, -v133, vcc
	ds_read_b128 v[196:199], v97 offset:2720
	s_waitcnt lgkmcnt(13)
	v_cmp_eq_u32_e64 s[0:1], 3, v1
	v_cmp_gt_u32_e32 vcc, 3, v1
	v_fma_f32 v132, v248, v144, 0
	v_fmac_f32_e32 v132, v145, v249
	v_fmac_f32_e32 v132, v146, v250
	v_cndmask_b32_e64 v251, 0, 1.0, s[0:1]
	v_cndmask_b32_e64 v251, v251, -v132, vcc
	ds_read_b128 v[200:203], v97 offset:2736
	s_waitcnt lgkmcnt(13)
	v_cmp_eq_u32_e64 s[0:1], 4, v1
	v_cmp_gt_u32_e32 vcc, 4, v1
	v_fma_f32 v133, v248, v148, 0
	v_fmac_f32_e32 v133, v149, v249
	v_fmac_f32_e32 v133, v150, v250
	v_fmac_f32_e32 v133, v151, v251
	v_cndmask_b32_e64 v252, 0, 1.0, s[0:1]
	v_cndmask_b32_e64 v252, v252, -v133, vcc
	ds_read_b128 v[204:207], v97 offset:2752
	s_waitcnt lgkmcnt(13)
	v_cmp_eq_u32_e64 s[0:1], 5, v1
	v_cmp_gt_u32_e32 vcc, 5, v1
	v_fma_f32 v132, v248, v152, 0
	v_fmac_f32_e32 v132, v153, v249
	v_fmac_f32_e32 v132, v154, v250
	v_fmac_f32_e32 v132, v155, v251
	ds_read_b128 v[208:211], v97 offset:2992
	s_waitcnt lgkmcnt(13)
	v_fmac_f32_e32 v132, v156, v252
	v_cndmask_b32_e64 v253, 0, 1.0, s[0:1]
	v_cndmask_b32_e64 v253, v253, -v132, vcc
	ds_read_b128 v[212:215], v97 offset:3008
	s_waitcnt lgkmcnt(13)
	v_cmp_eq_u32_e64 s[0:1], 6, v1
	v_cmp_gt_u32_e32 vcc, 6, v1
	v_fma_f32 v133, v248, v160, 0
	v_fmac_f32_e32 v133, v161, v249
	v_fmac_f32_e32 v133, v162, v250
	v_fmac_f32_e32 v133, v163, v251
	ds_read_b128 v[216:219], v97 offset:3024
	s_waitcnt lgkmcnt(13)
	v_fmac_f32_e32 v133, v164, v252
	v_fmac_f32_e32 v133, v165, v253
	v_cndmask_b32_e64 v254, 0, 1.0, s[0:1]
	v_cndmask_b32_e64 v254, v254, -v133, vcc
	ds_read_b128 v[64:67], v97 offset:3264
	s_waitcnt lgkmcnt(13)
	v_cmp_eq_u32_e64 s[0:1], 7, v1
	v_cmp_gt_u32_e32 vcc, 7, v1
	v_fma_f32 v132, v248, v168, 0
	v_fmac_f32_e32 v132, v169, v249
	v_fmac_f32_e32 v132, v170, v250
	v_fmac_f32_e32 v132, v171, v251
	ds_read_b128 v[68:71], v97 offset:3280
	s_waitcnt lgkmcnt(13)
	v_fmac_f32_e32 v132, v172, v252
	v_fmac_f32_e32 v132, v173, v253
	v_fmac_f32_e32 v132, v174, v254
	v_cndmask_b32_e64 v255, 0, 1.0, s[0:1]
	v_cndmask_b32_e64 v255, v255, -v132, vcc
	ds_read_b128 v[72:75], v97 offset:3296
	s_waitcnt lgkmcnt(13)
	v_cmp_eq_u32_e64 s[0:1], 8, v1
	v_cmp_gt_u32_e32 vcc, 8, v1
	v_fma_f32 v133, v248, v176, 0
	v_fmac_f32_e32 v133, v177, v249
	v_fmac_f32_e32 v133, v178, v250
	v_fmac_f32_e32 v133, v179, v251
	ds_read_b128 v[76:79], v97 offset:3536
	s_waitcnt lgkmcnt(13)
	v_fmac_f32_e32 v133, v180, v252
	v_fmac_f32_e32 v133, v181, v253
	v_fmac_f32_e32 v133, v182, v254
	v_fmac_f32_e32 v133, v183, v255
	v_cndmask_b32_e64 v240, 0, 1.0, s[0:1]
	v_cndmask_b32_e64 v240, v240, -v133, vcc
	ds_read_b128 v[80:83], v97 offset:3552
	s_waitcnt lgkmcnt(13)
	v_cmp_eq_u32_e64 s[0:1], 9, v1
	v_cmp_gt_u32_e32 vcc, 9, v1
	v_fma_f32 v132, v248, v184, 0
	v_fmac_f32_e32 v132, v185, v249
	v_fmac_f32_e32 v132, v186, v250
	v_fmac_f32_e32 v132, v187, v251
	ds_read_b128 v[84:87], v97 offset:3568
	s_waitcnt lgkmcnt(13)
; #define LAS __attribute__((address_space(3)))
; __device__ __forceinline__ void gdn_prep_item(LAS unsigned char* lds, int item, int b0, PrepRaw& R, int next_item, const bf16_t* qkv, const float* bg, const float* gconv_w, unsigned char* rec, float* gtarr) {
;     ...
;     if (tid < 64) { const int blk = tid >> 4, cidx = tid & 15; float x[16];
; #pragma unroll
;         for (int i = 0; i < 16; ++i) x[i] = (i == cidx) ? 1.f : 0.f;
; #pragma unroll
;         for (int i = 1; i < 16; ++i) { float a = 0.f; const LAS float* row = Lf + (16 * blk + i) * LS + 16 * blk;
; #pragma unroll
;             for (int j4 = 0; j4 < (i + 3) / 4; ++j4) { const f32x4 l4 = *(const LAS f32x4*)(row + 4 * j4);
; #pragma unroll
;                 for (int e = 0; e < 4; ++e) if (4 * j4 + e < i) a += l4[e] * x[4 * j4 + e]; }
;             if (i > cidx) x[i] = -a; }
; #pragma unroll
;         for (int i = 0; i < 16; ++i) Tf[(16 * blk + i) * LS + 16 * blk + cidx] = x[i];
;     }
	v_fmac_f32_e32 v132, v188, v252
	v_fmac_f32_e32 v132, v189, v253
	v_fmac_f32_e32 v132, v190, v254
	v_fmac_f32_e32 v132, v191, v255
	ds_read_b128 v[88:91], v97 offset:3584
	s_waitcnt lgkmcnt(13)
	v_fmac_f32_e32 v132, v192, v240
	v_cndmask_b32_e64 v241, 0, 1.0, s[0:1]
	v_cndmask_b32_e64 v241, v241, -v132, vcc
	ds_read_b128 v[92:95], v97 offset:3808
	s_waitcnt lgkmcnt(13)
	v_cmp_eq_u32_e64 s[0:1], 10, v1
	v_cmp_gt_u32_e32 vcc, 10, v1
	v_fma_f32 v133, v248, v196, 0
	v_fmac_f32_e32 v133, v197, v249
	v_fmac_f32_e32 v133, v198, v250
	v_fmac_f32_e32 v133, v199, v251
	ds_read_b128 v[120:123], v97 offset:3824
	s_waitcnt lgkmcnt(13)
	v_fmac_f32_e32 v133, v200, v252
	v_fmac_f32_e32 v133, v201, v253
	v_fmac_f32_e32 v133, v202, v254
	v_fmac_f32_e32 v133, v203, v255
	ds_read_b128 v[124:127], v97 offset:3840
	s_waitcnt lgkmcnt(13)
	v_fmac_f32_e32 v133, v204, v240
	v_fmac_f32_e32 v133, v205, v241
	v_cndmask_b32_e64 v242, 0, 1.0, s[0:1]
	v_cndmask_b32_e64 v242, v242, -v133, vcc
	ds_read_b128 v[128:131], v97 offset:3856
	s_waitcnt lgkmcnt(13)
	v_cmp_eq_u32_e64 s[0:1], 11, v1
	v_cmp_gt_u32_e32 vcc, 11, v1
	v_fma_f32 v132, v248, v208, 0
	v_fmac_f32_e32 v132, v209, v249
	v_fmac_f32_e32 v132, v210, v250
	v_fmac_f32_e32 v132, v211, v251
	ds_read_b128 v[222:225], v97 offset:4080
	s_waitcnt lgkmcnt(13)
	v_fmac_f32_e32 v132, v212, v252
	v_fmac_f32_e32 v132, v213, v253
	v_fmac_f32_e32 v132, v214, v254
	v_fmac_f32_e32 v132, v215, v255
	ds_read_b128 v[226:229], v97 offset:4096
	s_waitcnt lgkmcnt(13)
	v_fmac_f32_e32 v132, v216, v240
	v_fmac_f32_e32 v132, v217, v241
	v_fmac_f32_e32 v132, v218, v242
	v_cndmask_b32_e64 v243, 0, 1.0, s[0:1]
	v_cndmask_b32_e64 v243, v243, -v132, vcc
	ds_read_b128 v[230:233], v97 offset:4112
	s_waitcnt lgkmcnt(13)
	v_cmp_eq_u32_e64 s[0:1], 12, v1
	v_cmp_gt_u32_e32 vcc, 12, v1
	v_fma_f32 v133, v248, v64, 0
	v_fmac_f32_e32 v133, v65, v249
	v_fmac_f32_e32 v133, v66, v250
	v_fmac_f32_e32 v133, v67, v251
	ds_read_b128 v[234:237], v97 offset:4128
	s_waitcnt lgkmcnt(13)
	v_fmac_f32_e32 v133, v68, v252
	v_fmac_f32_e32 v133, v69, v253
	v_fmac_f32_e32 v133, v70, v254
	v_fmac_f32_e32 v133, v71, v255
	s_waitcnt lgkmcnt(12)
	v_fmac_f32_e32 v133, v72, v240
	v_fmac_f32_e32 v133, v73, v241
	v_fmac_f32_e32 v133, v74, v242
	v_fmac_f32_e32 v133, v75, v243
	v_cndmask_b32_e64 v102, 0, 1.0, s[0:1]
	v_cndmask_b32_e64 v102, v102, -v133, vcc
	s_waitcnt lgkmcnt(11)
	v_cmp_eq_u32_e64 s[0:1], 13, v1
	v_cmp_gt_u32_e32 vcc, 13, v1
	v_fma_f32 v132, v248, v76, 0
	v_fmac_f32_e32 v132, v77, v249
	v_fmac_f32_e32 v132, v78, v250
	v_fmac_f32_e32 v132, v79, v251
	s_waitcnt lgkmcnt(10)
	v_fmac_f32_e32 v132, v80, v252
	v_fmac_f32_e32 v132, v81, v253
	v_fmac_f32_e32 v132, v82, v254
	v_fmac_f32_e32 v132, v83, v255
	s_waitcnt lgkmcnt(9)
	v_fmac_f32_e32 v132, v84, v240
	v_fmac_f32_e32 v132, v85, v241
	v_fmac_f32_e32 v132, v86, v242
	v_fmac_f32_e32 v132, v87, v243
	s_waitcnt lgkmcnt(8)
	v_fmac_f32_e32 v132, v88, v102
	v_cndmask_b32_e64 v103, 0, 1.0, s[0:1]
	v_cndmask_b32_e64 v103, v103, -v132, vcc
	s_waitcnt lgkmcnt(7)
	v_cmp_eq_u32_e64 s[0:1], 14, v1
	v_cmp_gt_u32_e32 vcc, 14, v1
	v_fma_f32 v133, v248, v92, 0
	v_fmac_f32_e32 v133, v93, v249
	v_fmac_f32_e32 v133, v94, v250
	v_fmac_f32_e32 v133, v95, v251
	s_waitcnt lgkmcnt(6)
	v_fmac_f32_e32 v133, v120, v252
	v_fmac_f32_e32 v133, v121, v253
	v_fmac_f32_e32 v133, v122, v254
	v_fmac_f32_e32 v133, v123, v255
	s_waitcnt lgkmcnt(5)
	v_fmac_f32_e32 v133, v124, v240
	v_fmac_f32_e32 v133, v125, v241
	v_fmac_f32_e32 v133, v126, v242
	v_fmac_f32_e32 v133, v127, v243
	s_waitcnt lgkmcnt(4)
	v_fmac_f32_e32 v133, v128, v102
	v_fmac_f32_e32 v133, v129, v103
	v_cndmask_b32_e64 v104, 0, 1.0, s[0:1]
	v_cndmask_b32_e64 v104, v104, -v133, vcc
	s_waitcnt lgkmcnt(3)
	v_cmp_eq_u32_e64 s[0:1], 15, v1
	v_cmp_gt_u32_e32 vcc, 15, v1
	v_fma_f32 v132, v248, v222, 0
	v_fmac_f32_e32 v132, v223, v249
	v_fmac_f32_e32 v132, v224, v250
	v_fmac_f32_e32 v132, v225, v251
	s_waitcnt lgkmcnt(2)
	v_fmac_f32_e32 v132, v226, v252
	v_fmac_f32_e32 v132, v227, v253
	v_fmac_f32_e32 v132, v228, v254
	v_fmac_f32_e32 v132, v229, v255
	s_waitcnt lgkmcnt(1)
	v_fmac_f32_e32 v132, v230, v240
	v_fmac_f32_e32 v132, v231, v241
	v_fmac_f32_e32 v132, v232, v242
	v_fmac_f32_e32 v132, v233, v243
	s_waitcnt lgkmcnt(0)
	v_fmac_f32_e32 v132, v234, v102
	v_fmac_f32_e32 v132, v235, v103
	v_fmac_f32_e32 v132, v236, v104
	v_cndmask_b32_e64 v105, 0, 1.0, s[0:1]
	v_cndmask_b32_e64 v105, v105, -v132, vcc
	ds_write_b32 v119, v248
	ds_write_b32 v119, v249 offset:272
	ds_write_b32 v119, v250 offset:544
	ds_write_b32 v119, v251 offset:816
	ds_write_b32 v119, v252 offset:1088
	ds_write_b32 v119, v253 offset:1360
	ds_write_b32 v119, v254 offset:1632
	ds_write_b32 v119, v255 offset:1904
	ds_write_b32 v119, v240 offset:2176
	ds_write_b32 v119, v241 offset:2448
	ds_write_b32 v119, v242 offset:2720
	ds_write_b32 v119, v243 offset:2992
	ds_write_b32 v119, v102 offset:3264
	ds_write_b32 v119, v103 offset:3536
	ds_write_b32 v119, v104 offset:3808
	ds_write_b32 v119, v105 offset:4080
; #define LAS __attribute__((address_space(3)))
; __device__ __forceinline__ void gdn_prep_item(LAS unsigned char* lds, int item, int b0, PrepRaw& R, int next_item, const bf16_t* qkv, const float* bg, const float* gconv_w, unsigned char* rec, float* gtarr) {
;     ...
;     __syncthreads();
; #pragma unroll 1
;     for (int k = 1; k < 4; ++k) {
;         const int ntask = (4 - k) * 64;
;         if (tid < ntask) { const int bi = tid >> 6, r = (tid >> 2) & 15, cq = tid & 3, a = bi + k; f32x4 X = (f32x4){0.f, 0.f, 0.f, 0.f};
;             for (int m = bi; m < a; ++m)
; #pragma unroll
;                 for (int j4 = 0; j4 < 4; ++j4) { const f32x4 l4 = *(const LAS f32x4*)(Lf + (16 * a + r) * LS + 16 * m + 4 * j4);
; #pragma unroll
;                     for (int e = 0; e < 4; ++e) X += l4[e] * *(const LAS f32x4*)(Tf + (16 * m + 4 * j4 + e) * LS + 16 * bi + 4 * cq); }
;             *(LAS f32x4*)(Xs + bi * 256 + r * 16 + 4 * cq) = X; }
;         __syncthreads();
.LBB0_689:
	s_or_b64 exec, exec, s[6:7]
	s_add_i32 s0, 0, 0x1c400
	v_lshlrev_b32_e32 v6, 4, v99
	v_lshl_add_u32 v14, v100, 10, s0
	s_movk_i32 s0, 0x1140
	v_bfe_u32 v9, v99, 2, 4
	v_and_b32_e32 v2, 0xffffffc0, v99
	s_add_i32 s18, 0, 0x15c00
	v_and_b32_e32 v12, 48, v6
	v_mul_lo_u32 v3, v100, s0
	s_movk_i32 s19, 0x110
	s_movk_i32 s0, 0x1100
	v_add3_u32 v13, s18, v2, v12
	v_lshl_add_u32 v4, v9, 6, v14
	v_mad_u32_u24 v15, v9, s19, v3
	v_mad_u64_u32 v[2:3], s[0:1], v100, s0, v[2:3]
	v_lshrrev_b32_e32 v8, 2, v99
	v_or_b32_e32 v16, v2, v12
	s_mov_b32 s24, 1
	v_add_u32_e32 v17, v4, v12
	v_readfirstlane_b32 s98, v100
	v_and_b32_e32 v139, 15, v99
	v_bfe_u32 v137, v99, 4, 2
	v_lshlrev_b32_e32 v136, 8, v139
	v_lshl_add_u32 v136, v139, 4, v136
	v_lshl_add_u32 v136, v137, 4, v136
	v_lshlrev_b32_e32 v138, 10, v137
	v_lshl_add_u32 v138, v137, 6, v138
	v_lshl_add_u32 v137, v139, 2, v138
	s_mulk_i32 s98, 0x1140
	v_add_u32_e32 v138, 0x15c00, v136
	v_add_u32_e32 v136, 0x11800, v136
	v_add_u32_e32 v137, 0x15c00, v137
	v_add_u32_e32 v136, s98, v136
	v_add_u32_e32 v137, s98, v137
	v_add_u32_e32 v138, s98, v138
	s_waitcnt lgkmcnt(0)
	s_barrier
	s_cmpk_gt_u32 s98, 0x2280
	s_cbranch_scc1 .Llvl_1
	ds_read_b128 v[140:143], v136 offset:4352
	ds_read_b32 v152, v137
	ds_read_b32 v153, v137 offset:272
	ds_read_b32 v154, v137 offset:544
	ds_read_b32 v155, v137 offset:816
	ds_read_b128 v[164:167], v138 offset:4416
	s_waitcnt lgkmcnt(4)
	v_mfma_f32_16x16x4_f32 v[168:171], v140, v152, 0
	s_waitcnt lgkmcnt(3)
	v_mfma_f32_16x16x4_f32 v[168:171], v141, v153, v[168:171]
	s_waitcnt lgkmcnt(2)
	v_mfma_f32_16x16x4_f32 v[168:171], v142, v154, v[168:171]
	s_waitcnt lgkmcnt(1)
	v_mfma_f32_16x16x4_f32 v[168:171], v143, v155, v[168:171]
	s_waitcnt lgkmcnt(0)
	v_xor_b32_e32 v164, 0x80000000, v164
	v_xor_b32_e32 v165, 0x80000000, v165
	v_xor_b32_e32 v166, 0x80000000, v166
	v_xor_b32_e32 v167, 0x80000000, v167
	s_nop 5
	v_mfma_f32_16x16x4_f32 v[172:175], v164, v168, 0
	v_mfma_f32_16x16x4_f32 v[172:175], v165, v169, v[172:175]
	v_mfma_f32_16x16x4_f32 v[172:175], v166, v170, v[172:175]
	v_mfma_f32_16x16x4_f32 v[172:175], v167, v171, v[172:175]
	s_nop 7
	s_nop 1
	ds_write_b32 v137, v172 offset:4352
	ds_write_b32 v137, v173 offset:4624
	ds_write_b32 v137, v174 offset:4896
	ds_write_b32 v137, v175 offset:5168

; __global__ void __launch_bounds__(NTHREADS, 2) fwd_megakernel(Params p) {
	.amdhsa_kernel _Z14fwd_megakernel6Params
		.amdhsa_group_segment_fixed_size 0
		.amdhsa_private_segment_fixed_size 0
		.amdhsa_kernarg_size 448
		.amdhsa_user_sgpr_count 2
		.amdhsa_user_sgpr_dispatch_ptr 0
		.amdhsa_user_sgpr_queue_ptr 0
		.amdhsa_user_sgpr_kernarg_segment_ptr 1
		.amdhsa_user_sgpr_dispatch_id 0
		.amdhsa_user_sgpr_kernarg_preload_length 0
		.amdhsa_user_sgpr_kernarg_preload_offset 0
		.amdhsa_user_sgpr_private_segment_size 0
		.amdhsa_uses_dynamic_stack 0
		.amdhsa_enable_private_segment 0
		.amdhsa_system_sgpr_workgroup_id_x 1
		.amdhsa_system_sgpr_workgroup_id_y 0
		.amdhsa_system_sgpr_workgroup_id_z 0
		.amdhsa_system_sgpr_workgroup_info 0
		.amdhsa_system_vgpr_workitem_id 0
		.amdhsa_next_free_vgpr 256
		.amdhsa_next_free_sgpr 102
		.amdhsa_accum_offset 256
		.amdhsa_reserve_vcc 1
		.amdhsa_float_round_mode_32 0
		.amdhsa_float_round_mode_16_64 0
		.amdhsa_float_denorm_mode_32 3
		.amdhsa_float_denorm_mode_16_64 3
		.amdhsa_dx10_clamp 1
		.amdhsa_ieee_mode 1
		.amdhsa_fp16_overflow 0
		.amdhsa_tg_split 0
		.amdhsa_exception_fp_ieee_invalid_op 0
		.amdhsa_exception_fp_denorm_src 0
		.amdhsa_exception_fp_ieee_div_zero 0
		.amdhsa_exception_fp_ieee_overflow 0
		.amdhsa_exception_fp_ieee_underflow 0
		.amdhsa_exception_fp_ieee_inexact 0
		.amdhsa_exception_int_div_zero 0
	.end_amdhsa_kernel

; __global__ void __launch_bounds__(NTHREADS, 2) fwd_megakernel(Params p) {
amdhsa.kernels:
  - .agpr_count:     0
    .args:
      - .offset:         0
        .size:           192
        .value_kind:     by_value
      - .offset:         192
        .size:           4
        .value_kind:     hidden_block_count_x
      - .offset:         196
        .size:           4
        .value_kind:     hidden_block_count_y
      - .offset:         200
        .size:           4
        .value_kind:     hidden_block_count_z
      - .offset:         204
        .size:           2
        .value_kind:     hidden_group_size_x
      - .offset:         206
        .size:           2
        .value_kind:     hidden_group_size_y
      - .offset:         208
        .size:           2
        .value_kind:     hidden_group_size_z
      - .offset:         210
        .size:           2
        .value_kind:     hidden_remainder_x
      - .offset:         212
        .size:           2
        .value_kind:     hidden_remainder_y
      - .offset:         214
        .size:           2
        .value_kind:     hidden_remainder_z
      - .offset:         232
        .size:           8
        .value_kind:     hidden_global_offset_x
      - .offset:         240
        .size:           8
        .value_kind:     hidden_global_offset_y
      - .offset:         248
        .size:           8
        .value_kind:     hidden_global_offset_z
      - .offset:         256
        .size:           2
        .value_kind:     hidden_grid_dims
      - .offset:         312
        .size:           4
        .value_kind:     hidden_dynamic_lds_size
    .group_segment_fixed_size: 0
    .kernarg_segment_align: 8
    .kernarg_segment_size: 448
    .language:       OpenCL C
    .language_version:
      - 2
      - 0
    .max_flat_workgroup_size: 512
    .name:           _Z14fwd_megakernel6Params
    .private_segment_fixed_size: 0
    .sgpr_count:     108
    .sgpr_spill_count: 192
    .symbol:         _Z14fwd_megakernel6Params.kd
    .uniform_work_group_size: 1
    .uses_dynamic_stack: false
    .vgpr_count:     256
    .vgpr_spill_count: 0
    .wavefront_size: 64
